# P0 RMSNorm rows: gain vector loaded once before the row loop instead of a load + vmcnt(0) per column block
# speedup vs baseline: 1.0006x; 1.0006x over previous
; __device__ __forceinline__ void rms_rows2_to_bf16(const float* xa, bf16_t* oa, const float* xb, bf16_t* ob, bool hasb, const float* gain, int lane) {
;     const f32x4* ra = (const f32x4*)xa + lane; const f32x4* rb = (const f32x4*)(hasb ? xb : xa) + lane; const f32x4* gr = (const f32x4*)gain + lane;
; __global__ void __launch_bounds__(NTHREADS, 2) fox_fwd(Args args) {
;     ...
;         for (int m = gw; m < MREAL + NMETA; m += 2 * NGW) { const int m2 = m + NGW;
;             rms_rows2_to_bf16(m < MREAL ? x + (size_t)m * DM : meta + (size_t)(m - MREAL) * DM, XN + (size_t)m * DM,
;                               m2 < MREAL ? x + (size_t)m2 * DM : meta + (size_t)(m2 - MREAL) * DM, XN + (size_t)m2 * DM, m2 < MREAL + NMETA, norm_gain, lane); }
.LBB0_216:
	s_cmpk_gt_i32 s66, 0x200f
	s_cbranch_scc1 .LBB0_243
	s_waitcnt vmcnt(0)
	v_mbcnt_lo_u32_b32 v0, -1, 0
	v_mbcnt_hi_u32_b32 v0, -1, v0
	v_and_b32_e32 v1, 64, v0
	v_add_u32_e32 v1, 64, v1
	v_xor_b32_e32 v2, 1, v0
	v_cmp_lt_i32_e32 vcc, v2, v1
	v_readlane_b32 s8, v248, 7
	v_mov_b32_e32 v69, 0
	v_cndmask_b32_e32 v2, v0, v2, vcc
	v_lshlrev_b32_e32 v90, 2, v2
	v_xor_b32_e32 v2, 2, v0
	v_cmp_lt_i32_e32 vcc, v2, v1
	v_lshlrev_b32_e32 v68, 4, v136
	v_readlane_b32 s12, v248, 11
	v_cndmask_b32_e32 v2, v0, v2, vcc
	v_lshlrev_b32_e32 v91, 2, v2
	v_xor_b32_e32 v2, 4, v0
	v_cmp_lt_i32_e32 vcc, v2, v1
	v_readlane_b32 s13, v248, 12
	s_mov_b64 s[0:1], 0x1000
	v_cndmask_b32_e32 v2, v0, v2, vcc
	v_lshlrev_b32_e32 v92, 2, v2
	v_xor_b32_e32 v2, 8, v0
	v_cmp_lt_i32_e32 vcc, v2, v1
	v_lshl_add_u64 v[70:71], s[12:13], 0, v[68:69]
	v_lshl_add_u64 v[74:75], v[70:71], 0, s[0:1]
	v_cndmask_b32_e32 v2, v0, v2, vcc
	v_lshlrev_b32_e32 v93, 2, v2
	v_xor_b32_e32 v2, 16, v0
	v_cmp_lt_i32_e32 vcc, v2, v1
	s_mov_b64 s[0:1], 0x1400
	v_lshl_add_u64 v[76:77], v[70:71], 0, s[0:1]
	v_cndmask_b32_e32 v2, v0, v2, vcc
	v_lshlrev_b32_e32 v94, 2, v2
	v_xor_b32_e32 v2, 32, v0
	s_mov_b64 s[0:1], 0x1800
	v_cmp_lt_i32_e32 vcc, v2, v1
	v_readlane_b32 s9, v248, 8
	v_readlane_b32 s20, v248, 19
	v_readlane_b32 s21, v248, 20
	v_lshlrev_b32_e32 v68, 3, v136
	v_lshl_add_u64 v[78:79], v[70:71], 0, s[0:1]
	s_mov_b64 s[0:1], 0x1c00
	v_cndmask_b32_e32 v0, v0, v2, vcc
	v_lshl_add_u64 v[72:73], s[4:5], 0, v[68:69]
	v_lshl_add_u64 v[80:81], v[70:71], 0, s[0:1]
	s_mov_b32 s9, 0
	v_lshlrev_b32_e32 v95, 2, v0
	v_lshlrev_b32_e32 v68, 4, v136
	s_movk_i32 s20, 0x1000
	v_mov_b32_e32 v96, 0x358637bd
	s_mov_b32 s21, 0xf800000
	v_mov_b32_e32 v97, 0x260
	s_mov_b32 s0, s66
	v_readlane_b32 s10, v248, 9
	v_readlane_b32 s11, v248, 10
	v_readlane_b32 s14, v248, 13
	v_readlane_b32 s15, v248, 14
	v_readlane_b32 s16, v248, 15
	v_readlane_b32 s17, v248, 16
	v_readlane_b32 s18, v248, 17
	v_readlane_b32 s19, v248, 18
	v_readlane_b32 s22, v248, 21
	v_readlane_b32 s23, v248, 22
	global_load_dwordx4 v[144:147], v[70:71], off
	global_load_dwordx4 v[148:151], v[70:71], off offset:1024
	global_load_dwordx4 v[152:155], v[70:71], off offset:2048
	global_load_dwordx4 v[156:159], v[70:71], off offset:3072
	global_load_dwordx4 v[160:163], v[74:75], off
	global_load_dwordx4 v[164:167], v[76:77], off
	global_load_dwordx4 v[168:171], v[78:79], off
	global_load_dwordx4 v[172:175], v[80:81], off
	s_branch .LBB0_219

; __device__ __forceinline__ void rms_rows2_to_bf16(const float* xa, bf16_t* oa, const float* xb, bf16_t* ob, bool hasb, const float* gain, int lane) {
;     const f32x4* ra = (const f32x4*)xa + lane; const f32x4* rb = (const f32x4*)(hasb ? xb : xa) + lane; const f32x4* gr = (const f32x4*)gain + lane;
;     f32x4 v[8], w[8]; float s = 0.f, s2 = 0.f;
; #pragma unroll
;     for (int j = 0; j < 8; ++j) v[j] = __builtin_nontemporal_load(ra + 64 * j);
; #pragma unroll
;     for (int j = 0; j < 8; ++j) w[j] = __builtin_nontemporal_load(rb + 64 * j);
; #pragma unroll
;     for (int j = 0; j < 8; ++j) { s += (v[j].x * v[j].x + v[j].y * v[j].y) + (v[j].z * v[j].z + v[j].w * v[j].w); s2 += (w[j].x * w[j].x + w[j].y * w[j].y) + (w[j].z * w[j].z + w[j].w * w[j].w); }
;     const float rstd = 1.0f / sqrtf(wave_sum(s) * (1.f / DM) + EPS), rstd2 = 1.0f / sqrtf(wave_sum(s2) * (1.f / DM) + EPS);
.LBB0_227:
	v_lshl_add_u64 v[0:1], s[2:3], 0, v[68:69]
	s_lshl_b64 s[14:15], s[0:1], 12
	s_lshl_b64 s[16:17], s[10:11], 12
	global_load_dwordx4 v[60:63], v68, s[2:3] nt
	global_load_dwordx4 v[48:51], v68, s[2:3] offset:1024 nt
	global_load_dwordx4 v[44:47], v68, s[2:3] offset:2048 nt
	global_load_dwordx4 v[32:35], v68, s[2:3] offset:3072 nt
	v_add_co_u32_e32 v64, vcc, s20, v0
	s_cmpk_lt_i32 s10, 0x2010
	s_nop 0
	v_addc_co_u32_e32 v65, vcc, 0, v1, vcc
	s_cselect_b64 s[12:13], -1, 0
	global_load_dwordx4 v[28:31], v[64:65], off nt
	s_and_b64 s[0:1], s[12:13], exec
	s_cselect_b32 s0, s18, s2
	s_cselect_b32 s1, s19, s3
	global_load_dwordx4 v[56:59], v68, s[0:1] nt
	global_load_dwordx4 v[52:55], v68, s[0:1] offset:1024 nt
	global_load_dwordx4 v[40:43], v68, s[0:1] offset:2048 nt
	v_lshl_add_u64 v[0:1], s[0:1], 0, v[68:69]
	v_add_co_u32_e32 v66, vcc, s20, v0
	s_cmpk_gt_i32 s10, 0x200f
	s_nop 0
	v_addc_co_u32_e32 v67, vcc, 0, v1, vcc
	global_load_dwordx4 v[24:27], v[66:67], off nt
	global_load_dwordx4 v[36:39], v68, s[0:1] offset:3072 nt
	global_load_dwordx4 v[20:23], v[64:65], off offset:1024 nt
	global_load_dwordx4 v[4:7], v[64:65], off offset:3072 nt
	global_load_dwordx4 v[12:15], v[64:65], off offset:2048 nt
	global_load_dwordx4 v[16:19], v[66:67], off offset:1024 nt
	global_load_dwordx4 v[8:11], v[66:67], off offset:2048 nt
	global_load_dwordx4 v[0:3], v[66:67], off offset:3072 nt
	s_waitcnt vmcnt(15)
	v_mov_b32_e32 v66, v61
	s_waitcnt vmcnt(14)
	v_mov_b32_e32 v67, v49
	v_mov_b32_e32 v84, v63
	v_mov_b32_e32 v85, v51
	v_mov_b32_e32 v64, v60
	v_mov_b32_e32 v65, v48
	v_mov_b32_e32 v82, v62
	v_mov_b32_e32 v83, v50
	s_waitcnt vmcnt(13)
	v_pk_mul_f32 v[86:87], v[46:47], v[46:47]
	v_pk_mul_f32 v[88:89], v[44:45], v[44:45]
	s_waitcnt vmcnt(12)
	v_mul_f32_e32 v98, v33, v33
	v_mul_f32_e32 v100, v35, v35
	v_pk_mul_f32 v[66:67], v[66:67], v[66:67]
	v_pk_mul_f32 v[84:85], v[84:85], v[84:85]
	v_pk_mov_b32 v[102:103], v[88:89], v[86:87] op_sel:[1,0]
	v_mov_b32_e32 v89, v87
	v_pk_fma_f32 v[86:87], v[32:33], v[32:33], v[98:99] op_sel_hi:[1,1,0]
	v_pk_fma_f32 v[98:99], v[34:35], v[34:35], v[100:101] op_sel_hi:[1,1,0]
	v_pk_fma_f32 v[64:65], v[64:65], v[64:65], v[66:67]
	v_pk_fma_f32 v[66:67], v[82:83], v[82:83], v[84:85]
	v_pk_add_f32 v[82:83], v[102:103], v[88:89]
	s_waitcnt vmcnt(11)
	v_mul_f32_e32 v87, v30, v30
	v_mul_f32_e32 v99, v31, v31
	v_pk_add_f32 v[64:65], v[64:65], v[66:67]
	v_mul_f32_e32 v104, v28, v28
	v_mul_f32_e32 v84, v29, v29
	v_pk_add_f32 v[66:67], v[82:83], v[82:83] op_sel:[0,1] op_sel_hi:[1,0]
	v_pk_add_f32 v[64:65], v[64:65], v[64:65] op_sel:[0,1] op_sel_hi:[1,0]
	v_pk_add_f32 v[82:83], v[86:87], v[98:99]
	s_waitcnt vmcnt(10)
	v_mov_b32_e32 v86, v57
	s_waitcnt vmcnt(9)
	v_mov_b32_e32 v87, v53
	v_mov_b32_e32 v98, v59
	v_mov_b32_e32 v99, v55
	v_mov_b32_e32 v67, v84
	v_mov_b32_e32 v84, v56
	v_mov_b32_e32 v85, v52
	v_mov_b32_e32 v88, v58
	v_mov_b32_e32 v89, v54
	v_mov_b32_e32 v65, v104
	v_pk_mul_f32 v[86:87], v[86:87], v[86:87]
	v_pk_mul_f32 v[98:99], v[98:99], v[98:99]
	s_waitcnt vmcnt(8)
	v_pk_mul_f32 v[100:101], v[42:43], v[42:43]
	v_pk_mul_f32 v[102:103], v[40:41], v[40:41]
	v_pk_add_f32 v[64:65], v[64:65], v[66:67]
	v_pk_fma_f32 v[66:67], v[84:85], v[84:85], v[86:87]
	v_pk_fma_f32 v[84:85], v[88:89], v[88:89], v[98:99]
	v_pk_mov_b32 v[104:105], v[102:103], v[100:101] op_sel:[1,0]
	v_mov_b32_e32 v103, v101
	v_pk_add_f32 v[66:67], v[66:67], v[84:85]
	v_pk_add_f32 v[86:87], v[104:105], v[102:103]
	v_pk_add_f32 v[64:65], v[64:65], v[82:83]
	s_waitcnt vmcnt(7)
	v_mul_f32_e32 v82, v24, v24
	v_pk_add_f32 v[66:67], v[66:67], v[66:67] op_sel:[0,1] op_sel_hi:[1,0]
	v_mul_f32_e32 v88, v25, v25
	v_mov_b32_e32 v67, v82
	v_pk_add_f32 v[82:83], v[86:87], v[86:87] op_sel:[0,1] op_sel_hi:[1,0]
	s_waitcnt vmcnt(6)
	v_mul_f32_e32 v84, v39, v39
	v_mov_b32_e32 v83, v88
	v_pk_add_f32 v[66:67], v[66:67], v[82:83]
	v_mul_f32_e32 v82, v37, v37
	v_mul_f32_e32 v89, v26, v26
	v_mul_f32_e32 v98, v27, v27
	v_pk_fma_f32 v[82:83], v[36:37], v[36:37], v[82:83] op_sel_hi:[1,1,0]
	v_pk_fma_f32 v[84:85], v[38:39], v[38:39], v[84:85] op_sel_hi:[1,1,0]
	v_mov_b32_e32 v83, v89
	v_mov_b32_e32 v85, v98
	v_pk_add_f32 v[82:83], v[82:83], v[84:85]
	s_waitcnt vmcnt(5)
	v_pk_mul_f32 v[84:85], v[22:23], v[22:23]
	v_pk_mul_f32 v[86:87], v[20:21], v[20:21]
	v_pk_add_f32 v[64:65], v[64:65], v[64:65] op_sel:[0,1] op_sel_hi:[1,0]
	v_pk_mov_b32 v[88:89], v[86:87], v[84:85] op_sel:[1,0]
	v_mov_b32_e32 v87, v85
	v_pk_add_f32 v[84:85], v[88:89], v[86:87]
	s_waitcnt vmcnt(4)
	v_mul_f32_e32 v86, v4, v4
	v_mul_f32_e32 v87, v5, v5
	v_pk_add_f32 v[84:85], v[84:85], v[84:85] op_sel:[0,1] op_sel_hi:[1,0]
	v_mov_b32_e32 v65, v86
	v_mov_b32_e32 v85, v87
	v_pk_add_f32 v[64:65], v[64:65], v[84:85]
	s_waitcnt vmcnt(3)
	v_mul_f32_e32 v84, v13, v13
	v_mul_f32_e32 v86, v15, v15
	v_mul_f32_e32 v88, v6, v6
	v_mul_f32_e32 v89, v7, v7
	v_pk_fma_f32 v[84:85], v[12:13], v[12:13], v[84:85] op_sel_hi:[1,1,0]
	v_pk_fma_f32 v[86:87], v[14:15], v[14:15], v[86:87] op_sel_hi:[1,1,0]
	v_mov_b32_e32 v85, v88
	v_mov_b32_e32 v87, v89
	v_pk_add_f32 v[84:85], v[84:85], v[86:87]
	s_nop 0
	v_pk_add_f32 v[64:65], v[64:65], v[84:85]
	s_nop 0
	v_add_f32_e32 v86, v64, v65
	ds_bpermute_b32 v87, v90, v86
	v_pk_add_f32 v[64:65], v[66:67], v[82:83]
	s_waitcnt vmcnt(2)
	v_pk_mul_f32 v[66:67], v[18:19], v[18:19]
	v_pk_mul_f32 v[82:83], v[16:17], v[16:17]
	v_pk_add_f32 v[64:65], v[64:65], v[64:65] op_sel:[0,1] op_sel_hi:[1,0]
	s_waitcnt lgkmcnt(0)
	v_add_f32_e32 v86, v86, v87
	ds_bpermute_b32 v87, v91, v86
	v_pk_mov_b32 v[84:85], v[82:83], v[66:67] op_sel:[1,0]
	v_mov_b32_e32 v83, v67
	v_pk_add_f32 v[66:67], v[84:85], v[82:83]
	s_waitcnt vmcnt(0)
; __device__ __forceinline__ unsigned pk2(float lo, float hi) { return cvt_pk_bf16(lo, hi); }
; __device__ __forceinline__ void rms_rows2_to_bf16(const float* xa, bf16_t* oa, const float* xb, bf16_t* ob, bool hasb, const float* gain, int lane) {
;     ...
;     const float rstd = 1.0f / sqrtf(wave_sum(s) * (1.f / DM) + EPS), rstd2 = 1.0f / sqrtf(wave_sum(s2) * (1.f / DM) + EPS);
;     unsigned long long* o8 = (unsigned long long*)oa + lane; unsigned long long* p8 = (unsigned long long*)ob + lane;
; #pragma unroll
;     for (int j = 0; j < 8; ++j) { const f32x4 g = gr[64 * j]; const f32x4 y = v[j] * rstd * g, z = w[j] * rstd2 * g;
;         o8[64 * j] = (unsigned long long)pk2(y.x, y.y) | ((unsigned long long)pk2(y.z, y.w) << 32);
;         if (hasb) p8[64 * j] = (unsigned long long)pk2(z.x, z.y) | ((unsigned long long)pk2(z.z, z.w) << 32); }
	v_mul_f32_e32 v82, v0, v0
	s_waitcnt lgkmcnt(0)
	v_add_f32_e32 v84, v86, v87
	ds_bpermute_b32 v85, v92, v84
	v_mov_b32_e32 v65, v82
	v_mul_f32_e32 v83, v1, v1
	v_pk_add_f32 v[66:67], v[66:67], v[66:67] op_sel:[0,1] op_sel_hi:[1,0]
	v_mul_f32_e32 v86, v2, v2
	s_waitcnt lgkmcnt(0)
	v_add_f32_e32 v82, v84, v85
	ds_bpermute_b32 v84, v93, v82
	v_mov_b32_e32 v67, v83
	v_pk_add_f32 v[64:65], v[64:65], v[66:67]
	v_mul_f32_e32 v66, v9, v9
	v_mul_f32_e32 v87, v3, v3
	s_waitcnt lgkmcnt(0)
	v_add_f32_e32 v84, v82, v84
	ds_bpermute_b32 v85, v94, v84
	v_mul_f32_e32 v82, v11, v11
	v_pk_fma_f32 v[66:67], v[8:9], v[8:9], v[66:67] op_sel_hi:[1,1,0]
	v_pk_fma_f32 v[82:83], v[10:11], v[10:11], v[82:83] op_sel_hi:[1,1,0]
	v_mov_b32_e32 v67, v86
	s_waitcnt lgkmcnt(0)
	v_add_f32_e32 v84, v84, v85
	ds_bpermute_b32 v85, v95, v84
	v_mov_b32_e32 v83, v87
	v_pk_add_f32 v[66:67], v[66:67], v[82:83]
	s_nop 0
	v_pk_add_f32 v[64:65], v[64:65], v[66:67]
	s_nop 0
	v_add_f32_e32 v82, v64, v65
	s_waitcnt lgkmcnt(0)
	v_add_f32_e32 v64, v84, v85
	v_fmamk_f32 v64, v64, 0x3a000000, v96
	v_mul_f32_e32 v65, 0x4f800000, v64
	v_cmp_gt_f32_e32 vcc, s21, v64
	ds_bpermute_b32 v85, v90, v82
	s_waitcnt lgkmcnt(0)
	v_add_f32_e32 v82, v82, v85
	v_cndmask_b32_e32 v83, v64, v65, vcc
	ds_bpermute_b32 v85, v91, v82
	v_sqrt_f32_e32 v84, v83
	s_waitcnt lgkmcnt(0)
	v_add_f32_e32 v82, v82, v85
	ds_bpermute_b32 v85, v92, v82
	v_add_u32_e32 v86, -1, v84
	v_fma_f32 v87, -v86, v84, v83
	v_cmp_ge_f32_e64 s[0:1], 0, v87
	v_add_u32_e32 v87, 1, v84
	s_waitcnt lgkmcnt(0)
	v_add_f32_e32 v82, v82, v85
	ds_bpermute_b32 v85, v93, v82
	v_cndmask_b32_e64 v86, v84, v86, s[0:1]
	v_fma_f32 v84, -v87, v84, v83
	v_cmp_lt_f32_e64 s[0:1], 0, v84
	s_waitcnt lgkmcnt(0)
	v_add_f32_e32 v82, v82, v85
	ds_bpermute_b32 v85, v94, v82
	v_cndmask_b32_e64 v84, v86, v87, s[0:1]
	v_mul_f32_e32 v86, 0x37800000, v84
	v_cndmask_b32_e32 v84, v84, v86, vcc
	v_cmp_class_f32_e32 vcc, v83, v97
	s_waitcnt lgkmcnt(0)
	v_add_f32_e32 v82, v82, v85
	ds_bpermute_b32 v85, v95, v82
	v_cndmask_b32_e32 v83, v84, v83, vcc
	v_div_scale_f32 v84, s[0:1], v83, v83, 1.0
	v_rcp_f32_e32 v86, v84
	s_waitcnt lgkmcnt(0)
	v_add_f32_e32 v82, v82, v85
	v_fmamk_f32 v82, v82, 0x3a000000, v96
	v_mul_f32_e32 v85, 0x4f800000, v82
	v_cmp_gt_f32_e64 s[0:1], s21, v82
	v_fma_f32 v87, -v84, v86, 1.0
	v_fmac_f32_e32 v86, v87, v86
	v_cndmask_b32_e64 v82, v82, v85, s[0:1]
	v_div_scale_f32 v87, vcc, 1.0, v83, 1.0
	v_sqrt_f32_e32 v85, v82
	v_mul_f32_e32 v88, v87, v86
	v_fma_f32 v89, -v84, v88, v87
	v_fmac_f32_e32 v88, v89, v86
	v_fma_f32 v84, -v84, v88, v87
	v_add_u32_e32 v87, -1, v85
	v_fma_f32 v89, -v87, v85, v82
	v_cmp_ge_f32_e64 s[2:3], 0, v89
	v_add_u32_e32 v89, 1, v85
	v_div_fmas_f32 v84, v84, v86, v88
	v_cndmask_b32_e64 v87, v85, v87, s[2:3]
	v_fma_f32 v85, -v89, v85, v82
	v_cmp_lt_f32_e64 s[2:3], 0, v85
	v_div_fixup_f32 v88, v84, v83, 1.0
	v_pk_mul_f32 v[60:61], v[60:61], v[88:89] op_sel_hi:[1,0]
	v_cndmask_b32_e64 v85, v87, v89, s[2:3]
	v_mul_f32_e32 v87, 0x37800000, v85
	v_cndmask_b32_e64 v85, v85, v87, s[0:1]
	v_cmp_class_f32_e64 s[0:1], v82, v97
	v_pk_mul_f32 v[62:63], v[62:63], v[88:89] op_sel_hi:[1,0]
	v_mov_b32_e32 v64, v144
	v_mov_b32_e32 v65, v145
	v_mov_b32_e32 v66, v146
	v_mov_b32_e32 v67, v147
	v_pk_mul_f32 v[60:61], v[64:65], v[60:61]
	v_cndmask_b32_e64 v82, v85, v82, s[0:1]
	v_div_scale_f32 v85, s[0:1], v82, v82, 1.0
	v_rcp_f32_e32 v87, v85
	v_pk_mul_f32 v[62:63], v[66:67], v[62:63]
	v_cvt_pk_bf16_f32 v60, v60, v61
	v_fma_f32 v83, -v85, v87, 1.0
	v_fmac_f32_e32 v87, v83, v87
	v_div_scale_f32 v83, vcc, 1.0, v82, 1.0
	v_mul_f32_e32 v84, v83, v87
	v_fma_f32 v86, -v85, v84, v83
	v_fmac_f32_e32 v84, v86, v87
	v_fma_f32 v83, -v85, v84, v83
	v_div_fmas_f32 v83, v83, v87, v84
	v_div_fixup_f32 v84, v83, v82, 1.0
	v_lshl_add_u64 v[86:87], v[72:73], 0, s[14:15]
	v_lshl_add_u64 v[82:83], v[72:73], 0, s[16:17]
	v_mov_b32_e32 v85, v84
	v_cvt_pk_bf16_f32 v61, v62, v63
	global_store_dwordx2 v[86:87], v[60:61], off
	s_cbranch_scc1 .LBB0_229
	v_mov_b32_e32 v60, v84
	v_mov_b32_e32 v61, v84
	v_pk_mul_f32 v[56:57], v[56:57], v[84:85]
	v_pk_mul_f32 v[58:59], v[58:59], v[60:61]
	v_pk_mul_f32 v[56:57], v[64:65], v[56:57]
	v_pk_mul_f32 v[58:59], v[66:67], v[58:59]
	v_cvt_pk_bf16_f32 v56, v56, v57
	s_nop 0
	v_cvt_pk_bf16_f32 v57, v58, v59
	global_store_dwordx2 v[82:83], v[56:57], off
.LBB0_229:
	v_mov_b32_e32 v89, v88
	v_mov_b32_e32 v60, v88
	v_mov_b32_e32 v61, v88
	v_cndmask_b32_e64 v62, 0, 1, s[12:13]
	v_pk_mul_f32 v[48:49], v[48:49], v[88:89]
	v_pk_mul_f32 v[50:51], v[50:51], v[60:61]
	v_cmp_ne_u32_e64 s[0:1], 1, v62
	s_andn2_b64 vcc, exec, s[12:13]
	v_mov_b32_e32 v56, v148
	v_mov_b32_e32 v57, v149
	v_mov_b32_e32 v58, v150
	v_mov_b32_e32 v59, v151
	v_pk_mul_f32 v[48:49], v[48:49], v[56:57]
	v_pk_mul_f32 v[50:51], v[50:51], v[58:59]
	v_cvt_pk_bf16_f32 v48, v48, v49
	s_nop 0
	v_cvt_pk_bf16_f32 v49, v50, v51
	global_store_dwordx2 v[86:87], v[48:49], off offset:512
	s_cbranch_vccnz .LBB0_231
	v_mov_b32_e32 v48, v84
	v_mov_b32_e32 v49, v84
	v_pk_mul_f32 v[50:51], v[52:53], v[84:85]
	v_pk_mul_f32 v[48:49], v[54:55], v[48:49]
	v_pk_mul_f32 v[50:51], v[50:51], v[56:57]
	v_pk_mul_f32 v[48:49], v[48:49], v[58:59]
	v_cvt_pk_bf16_f32 v50, v50, v51
	s_nop 0
	v_cvt_pk_bf16_f32 v51, v48, v49
	global_store_dwordx2 v[82:83], v[50:51], off offset:512
; __device__ __forceinline__ unsigned pk2(float lo, float hi) { return cvt_pk_bf16(lo, hi); }
; __device__ __forceinline__ void rms_rows2_to_bf16(const float* xa, bf16_t* oa, const float* xb, bf16_t* ob, bool hasb, const float* gain, int lane) {
;     ...
;     for (int j = 0; j < 8; ++j) { const f32x4 g = gr[64 * j]; const f32x4 y = v[j] * rstd * g, z = w[j] * rstd2 * g;
;         o8[64 * j] = (unsigned long long)pk2(y.x, y.y) | ((unsigned long long)pk2(y.z, y.w) << 32);
;         if (hasb) p8[64 * j] = (unsigned long long)pk2(z.x, z.y) | ((unsigned long long)pk2(z.z, z.w) << 32); }
.LBB0_231:
	v_pk_mul_f32 v[44:45], v[44:45], v[88:89]
	v_pk_mul_f32 v[46:47], v[46:47], v[60:61]
	s_and_b64 vcc, exec, s[0:1]
	v_mov_b32_e32 v48, v152
	v_mov_b32_e32 v49, v153
	v_mov_b32_e32 v50, v154
	v_mov_b32_e32 v51, v155
	v_pk_mul_f32 v[44:45], v[44:45], v[48:49]
	v_pk_mul_f32 v[46:47], v[46:47], v[50:51]
	v_cvt_pk_bf16_f32 v44, v44, v45
	s_nop 0
	v_cvt_pk_bf16_f32 v45, v46, v47
	global_store_dwordx2 v[86:87], v[44:45], off offset:1024
	s_cbranch_vccnz .LBB0_233
	v_mov_b32_e32 v44, v84
	v_mov_b32_e32 v45, v84
	v_pk_mul_f32 v[40:41], v[40:41], v[84:85]
	v_pk_mul_f32 v[42:43], v[42:43], v[44:45]
	v_pk_mul_f32 v[40:41], v[40:41], v[48:49]
	v_pk_mul_f32 v[42:43], v[42:43], v[50:51]
	v_cvt_pk_bf16_f32 v40, v40, v41
	s_nop 0
	v_cvt_pk_bf16_f32 v41, v42, v43
	global_store_dwordx2 v[82:83], v[40:41], off offset:1024
.LBB0_233:
	v_mov_b32_e32 v44, v88
	v_mov_b32_e32 v45, v88
	v_pk_mul_f32 v[32:33], v[32:33], v[88:89]
	v_pk_mul_f32 v[34:35], v[34:35], v[44:45]
	s_and_b64 vcc, exec, s[0:1]
	v_mov_b32_e32 v40, v156
	v_mov_b32_e32 v41, v157
	v_mov_b32_e32 v42, v158
	v_mov_b32_e32 v43, v159
	v_pk_mul_f32 v[32:33], v[32:33], v[40:41]
	v_pk_mul_f32 v[34:35], v[34:35], v[42:43]
	v_cvt_pk_bf16_f32 v32, v32, v33
	s_nop 0
	v_cvt_pk_bf16_f32 v33, v34, v35
	global_store_dwordx2 v[86:87], v[32:33], off offset:1536
	s_cbranch_vccnz .LBB0_235
	v_mov_b32_e32 v32, v84
	v_mov_b32_e32 v33, v84
	v_pk_mul_f32 v[34:35], v[36:37], v[84:85]
	v_pk_mul_f32 v[32:33], v[38:39], v[32:33]
	v_pk_mul_f32 v[34:35], v[34:35], v[40:41]
	v_pk_mul_f32 v[32:33], v[32:33], v[42:43]
	v_cvt_pk_bf16_f32 v34, v34, v35
	s_nop 0
	v_cvt_pk_bf16_f32 v35, v32, v33
	global_store_dwordx2 v[82:83], v[34:35], off offset:1536
.LBB0_235:
	v_pk_mul_f32 v[28:29], v[28:29], v[88:89]
	v_pk_mul_f32 v[30:31], v[30:31], v[44:45]
	s_and_b64 vcc, exec, s[0:1]
	v_mov_b32_e32 v32, v160
	v_mov_b32_e32 v33, v161
	v_mov_b32_e32 v34, v162
	v_mov_b32_e32 v35, v163
	v_pk_mul_f32 v[28:29], v[28:29], v[32:33]
	v_pk_mul_f32 v[30:31], v[30:31], v[34:35]
	v_cvt_pk_bf16_f32 v28, v28, v29
	s_nop 0
	v_cvt_pk_bf16_f32 v29, v30, v31
	global_store_dwordx2 v[86:87], v[28:29], off offset:2048
	s_cbranch_vccnz .LBB0_237
	v_mov_b32_e32 v28, v84
	v_mov_b32_e32 v29, v84
	v_pk_mul_f32 v[24:25], v[24:25], v[84:85]
	v_pk_mul_f32 v[26:27], v[26:27], v[28:29]
	v_pk_mul_f32 v[24:25], v[24:25], v[32:33]
	v_pk_mul_f32 v[26:27], v[26:27], v[34:35]
	v_cvt_pk_bf16_f32 v24, v24, v25
	s_nop 0
	v_cvt_pk_bf16_f32 v25, v26, v27
	global_store_dwordx2 v[82:83], v[24:25], off offset:2048
.LBB0_237:
	v_mov_b32_e32 v28, v88
	v_mov_b32_e32 v29, v88
	v_pk_mul_f32 v[20:21], v[20:21], v[88:89]
	v_pk_mul_f32 v[22:23], v[22:23], v[28:29]
	s_and_b64 vcc, exec, s[0:1]
	v_mov_b32_e32 v24, v164
	v_mov_b32_e32 v25, v165
	v_mov_b32_e32 v26, v166
	v_mov_b32_e32 v27, v167
	v_pk_mul_f32 v[20:21], v[20:21], v[24:25]
	v_pk_mul_f32 v[22:23], v[22:23], v[26:27]
	v_cvt_pk_bf16_f32 v20, v20, v21
	s_nop 0
	v_cvt_pk_bf16_f32 v21, v22, v23
	global_store_dwordx2 v[86:87], v[20:21], off offset:2560
	s_cbranch_vccnz .LBB0_239
	v_mov_b32_e32 v20, v84
	v_mov_b32_e32 v21, v84
	v_pk_mul_f32 v[16:17], v[16:17], v[84:85]
	v_pk_mul_f32 v[18:19], v[18:19], v[20:21]
	v_pk_mul_f32 v[16:17], v[16:17], v[24:25]
	v_pk_mul_f32 v[18:19], v[18:19], v[26:27]
	v_cvt_pk_bf16_f32 v16, v16, v17
	s_nop 0
	v_cvt_pk_bf16_f32 v17, v18, v19
	global_store_dwordx2 v[82:83], v[16:17], off offset:2560
.LBB0_239:
	v_pk_mul_f32 v[12:13], v[12:13], v[88:89]
	v_pk_mul_f32 v[14:15], v[14:15], v[28:29]
	s_and_b64 vcc, exec, s[0:1]
	v_mov_b32_e32 v16, v168
	v_mov_b32_e32 v17, v169
	v_mov_b32_e32 v18, v170
	v_mov_b32_e32 v19, v171
	v_pk_mul_f32 v[12:13], v[12:13], v[16:17]
	v_pk_mul_f32 v[14:15], v[14:15], v[18:19]
	v_cvt_pk_bf16_f32 v12, v12, v13
	s_nop 0
	v_cvt_pk_bf16_f32 v13, v14, v15
	global_store_dwordx2 v[86:87], v[12:13], off offset:3072
	s_cbranch_vccnz .LBB0_241
	v_mov_b32_e32 v12, v84
	v_mov_b32_e32 v13, v84
	v_pk_mul_f32 v[8:9], v[8:9], v[84:85]
	v_pk_mul_f32 v[10:11], v[10:11], v[12:13]
	v_pk_mul_f32 v[8:9], v[8:9], v[16:17]
	v_pk_mul_f32 v[10:11], v[10:11], v[18:19]
	v_cvt_pk_bf16_f32 v8, v8, v9
	s_nop 0
	v_cvt_pk_bf16_f32 v9, v10, v11
	global_store_dwordx2 v[82:83], v[8:9], off offset:3072
.LBB0_241:
	v_mov_b32_e32 v12, v88
	v_mov_b32_e32 v13, v88
	v_pk_mul_f32 v[4:5], v[4:5], v[88:89]
	v_pk_mul_f32 v[6:7], v[6:7], v[12:13]
	s_and_b64 vcc, exec, s[0:1]
	v_mov_b32_e32 v8, v172
	v_mov_b32_e32 v9, v173
	v_mov_b32_e32 v10, v174
	v_mov_b32_e32 v11, v175
	v_pk_mul_f32 v[4:5], v[4:5], v[8:9]
	v_pk_mul_f32 v[6:7], v[6:7], v[10:11]
	v_cvt_pk_bf16_f32 v4, v4, v5
	s_nop 0
	v_cvt_pk_bf16_f32 v5, v6, v7
	global_store_dwordx2 v[86:87], v[4:5], off offset:3584
	s_cbranch_vccnz .LBB0_218
	v_mov_b32_e32 v4, v84
	v_mov_b32_e32 v5, v84
	v_pk_mul_f32 v[0:1], v[0:1], v[84:85]
	v_pk_mul_f32 v[2:3], v[2:3], v[4:5]
	v_pk_mul_f32 v[0:1], v[0:1], v[8:9]
	v_pk_mul_f32 v[2:3], v[2:3], v[10:11]
	v_cvt_pk_bf16_f32 v0, v0, v1
	s_nop 0
	v_cvt_pk_bf16_f32 v1, v2, v3
	global_store_dwordx2 v[82:83], v[0:1], off offset:3584
	s_branch .LBB0_218
